# merge-first role from the hardware workgroup slot parity (HW_ID TG_ID bit 0) instead of block id bit 3
# speedup vs baseline: 1.0136x; 1.0136x over previous
.LBB0_117:
	s_or_b64 exec, exec, s[52:53]
	s_add_u32 s12, s94, 0x20c0000
	s_addc_u32 s13, s95, 0
	s_add_u32 s0, s94, 0x48e8000
	s_addc_u32 s1, s95, 0
	s_getreg_b32 s14, hwreg(HW_REG_HW_ID, 16, 4)
	s_and_b32 s14, s14, 1
	v_writelane_b32 v238, s0, 38
	s_cmpk_lt_i32 s64, 0xa00
	s_mov_b32 s97, 0
	v_writelane_b32 v238, s1, 39
	s_cselect_b64 s[0:1], -1, 0
	v_writelane_b32 v238, s0, 40
	s_mov_b32 s3, s97
	v_lshl_add_u64 v[0:1], v[0:1], 2, s[50:51]
	v_writelane_b32 v238, s1, 41
	s_add_u32 s0, s94, 0x130e8000
	s_addc_u32 s1, s95, 0
	v_writelane_b32 v238, s0, 42
	s_waitcnt lgkmcnt(0)
	s_barrier
	v_writelane_b32 v238, s1, 43
	s_add_u32 s0, s94, 0x120e8000
	s_addc_u32 s1, s95, 0
	v_writelane_b32 v238, s0, 44
	v_mov_b32_e32 v216, 0x168e8000
	s_nop 0
	v_writelane_b32 v238, s1, 45
	s_add_u32 s0, s94, 0x110e8000
	s_addc_u32 s1, s95, 0
	s_add_u32 s74, s94, 0xf8e8000
	v_writelane_b32 v238, s0, 46
	s_addc_u32 s75, s95, 0
	v_mov_b32_e32 v217, 0x138e8000
	v_writelane_b32 v238, s1, 47
	s_add_u32 s0, s94, 0xe0e8000
	s_addc_u32 s1, s95, 0
	v_writelane_b32 v238, s0, 48
	v_mov_b32_e32 v165, 0
	v_mov_b32_e32 v218, 1
	v_writelane_b32 v238, s1, 49
	s_add_u32 s0, s94, 0xc8e8000
	s_addc_u32 s1, s95, 0
	v_writelane_b32 v238, s0, 50
	s_cmpk_lt_i32 s64, 0x80
	v_mov_b32_e32 v219, 0x3ecc95a3
	v_writelane_b32 v238, s1, 51
	s_cselect_b64 s[0:1], -1, 0
	v_writelane_b32 v238, s0, 52
	s_add_u32 s15, s94, 0x1e80000
	v_mov_b32_e32 v220, 1.0
	v_writelane_b32 v238, s1, 53
	s_addc_u32 s0, s95, 0
	s_add_u32 s90, s94, 0x24c0000
	s_addc_u32 s91, s95, 0
	v_writelane_b32 v238, s0, 54
	s_add_u32 s0, s94, 0x88e8000
	s_addc_u32 s1, s95, 0
	v_writelane_b32 v238, s0, 55
	s_cmpk_lt_i32 s64, 0x200
	v_mov_b32_e32 v166, 0x12000
	v_writelane_b32 v238, s1, 56
	s_cselect_b64 s[0:1], -1, 0
	s_add_u32 s6, s94, 0x1b148000
	s_addc_u32 s7, s95, 0
	s_add_u32 s85, s94, 0x1b948000
	s_addc_u32 s33, s95, 0
	s_add_u32 s28, s94, 0x1c948000
	v_writelane_b32 v238, s0, 57
	s_addc_u32 s29, s95, 0
	s_lshl_b64 s[34:35], s[2:3], 11
	v_writelane_b32 v238, s1, 58
	s_add_u32 s0, s94, 0x1a00000
	s_addc_u32 s1, s95, 0
	v_writelane_b32 v238, s0, 59
	v_mov_b32_e32 v168, 0x12004
	v_mov_b32_e32 v221, 0xf149f2ca
	v_writelane_b32 v238, s1, 60
	s_add_u32 s0, s94, 0x1800000
	s_addc_u32 s1, s95, 0
	v_writelane_b32 v238, s0, 61
	v_mov_b32_e32 v222, 0x41b17218
	v_mov_b32_e32 v223, 0x7f800000
	v_writelane_b32 v238, s1, 62
	s_add_u32 s0, s94, 0x1700000
	s_addc_u32 s1, s95, 0
	v_writelane_b32 v238, s0, 63
	v_mov_b32_e32 v224, 0x7fc00000
	v_readlane_b32 s48, v238, 20
	v_writelane_b32 v237, s1, 0
	s_add_u32 s0, s94, 0x1500000
	s_addc_u32 s1, s95, 0
	v_writelane_b32 v237, s0, 1
	v_readlane_b32 s54, v238, 26
	v_readlane_b32 s55, v238, 27
	v_writelane_b32 v237, s1, 2
	s_add_u32 s0, s94, 0x1400000
	s_addc_u32 s1, s95, 0
	v_writelane_b32 v237, s0, 3
	v_readlane_b32 s49, v238, 21
	v_readlane_b32 s50, v238, 22
	v_writelane_b32 v237, s1, 4
	s_add_u32 s0, s94, 0x48e1200
	s_addc_u32 s1, s95, 0
	s_add_u32 s8, s94, 0x48e1400
	s_addc_u32 s9, s95, 0
	s_add_u32 s20, s94, 0x48e1500
	s_addc_u32 s21, s95, 0
	s_add_u32 s16, s94, 0x48e1600
	v_writelane_b32 v237, s0, 5
	s_addc_u32 s17, s95, 0
	s_add_u32 s18, s94, 0x48e1700
	v_writelane_b32 v237, s1, 6
	s_mov_b64 s[0:1], 0x1400
	v_lshl_add_u64 v[162:163], v[0:1], 0, s[0:1]
	s_mov_b64 s[0:1], 0x2400
	s_addc_u32 s19, s95, 0
	v_lshl_add_u64 v[160:161], v[0:1], 0, s[0:1]
	s_add_u32 s0, s94, 0x48e1800
	s_addc_u32 s1, s95, 0
	v_writelane_b32 v237, s0, 7
	v_readlane_b32 s51, v238, 23
	v_mbcnt_lo_u32_b32 v0, -1, 0
	v_writelane_b32 v237, s1, 8
	s_add_u32 s0, s94, 0x48e1900
	s_addc_u32 s1, s95, 0
	v_writelane_b32 v237, s0, 9
	v_readlane_b32 s52, v238, 24
	v_readlane_b32 s53, v238, 25
	v_writelane_b32 v237, s1, 10
	s_add_u32 s0, s94, 0x48e1a00
	s_addc_u32 s1, s95, 0
	v_writelane_b32 v237, s0, 11
	v_readlane_b32 s56, v238, 28
	v_readlane_b32 s57, v238, 29
	v_writelane_b32 v237, s1, 12
	s_add_u32 s0, s94, 0x48e1b00
	s_addc_u32 s1, s95, 0
	v_writelane_b32 v237, s0, 13
	v_readlane_b32 s58, v238, 30
	v_readlane_b32 s59, v238, 31
	v_writelane_b32 v237, s1, 14
	s_add_u32 s0, s94, 0x48e1c00
	s_addc_u32 s1, s95, 0
	v_writelane_b32 v237, s0, 15
	v_readlane_b32 s60, v238, 32
	v_readlane_b32 s61, v238, 33
	v_writelane_b32 v237, s1, 16
	s_add_u32 s0, s94, 0x48e1d00
	s_addc_u32 s1, s95, 0
	v_writelane_b32 v237, s0, 17
	v_readlane_b32 s62, v238, 34
	v_readlane_b32 s63, v238, 35
	v_writelane_b32 v237, s1, 18
	s_add_u32 s0, s94, 0x48e1e00
	s_addc_u32 s1, s95, 0
	v_writelane_b32 v237, s0, 19
	v_mbcnt_hi_u32_b32 v215, -1, v0
	v_mov_b32_e32 v225, 0xff800000
	v_writelane_b32 v237, s1, 20
	s_add_u32 s0, s94, 0x48e1f00
	s_addc_u32 s1, s95, 0
	v_writelane_b32 v237, s0, 21
	s_mov_b32 s88, 0xfffffc0
	s_movk_i32 s89, 0x90
	v_writelane_b32 v237, s1, 22
	s_add_u32 s0, s94, 0x48e2000
	s_addc_u32 s1, s95, 0
	v_writelane_b32 v237, s0, 23
	s_movk_i32 s70, 0x210
	s_movk_i32 s71, 0x1800
	v_writelane_b32 v237, s1, 24
	s_add_u32 s0, s94, 0x48e2100
	s_addc_u32 s1, s95, 0
	v_writelane_b32 v237, s0, 25
	s_mov_b32 s26, 0x10000
	s_mov_b32 s27, 0x20000
	v_writelane_b32 v237, s1, 26
	s_add_u32 s0, s94, 0x48e2200
	s_addc_u32 s1, s95, 0
	v_writelane_b32 v237, s0, 27
	s_mov_b32 s84, 0x30000
	s_nop 0
	v_writelane_b32 v237, s1, 28
	s_add_u32 s0, s94, 0x48e2300
	s_addc_u32 s1, s95, 0
	v_writelane_b32 v237, s0, 29
	s_cmp_eq_u32 s30, 0
	s_nop 0
	v_writelane_b32 v237, s1, 30
	s_cselect_b64 s[0:1], -1, 0
	v_writelane_b32 v237, s0, 31
	s_cmp_eq_u32 s30, 1
	s_nop 0
	v_writelane_b32 v237, s1, 32
	s_cselect_b64 s[0:1], -1, 0
	v_writelane_b32 v237, s0, 33
	s_cmp_eq_u32 s30, 2
	s_nop 0
	v_writelane_b32 v237, s1, 34
	s_cselect_b64 s[0:1], -1, 0
	v_writelane_b32 v237, s0, 35
	s_cmp_eq_u32 s30, 3
	s_nop 0
	v_writelane_b32 v237, s1, 36
	s_cselect_b64 s[0:1], -1, 0
	v_writelane_b32 v237, s0, 37
	s_cmp_eq_u32 s30, 4
	s_nop 0
	v_writelane_b32 v237, s1, 38
	s_cselect_b64 s[0:1], -1, 0
	v_writelane_b32 v237, s0, 39
	s_cmp_eq_u32 s30, 5
	s_nop 0
	v_writelane_b32 v237, s1, 40
	s_cselect_b64 s[0:1], -1, 0
	v_writelane_b32 v237, s0, 41
	s_cmp_eq_u32 s30, 6
	s_nop 0
	v_writelane_b32 v237, s1, 42
	s_cselect_b64 s[0:1], -1, 0
	v_writelane_b32 v237, s0, 43
	s_cmp_eq_u32 s30, 7
	s_nop 0
	v_writelane_b32 v237, s1, 44
	s_cselect_b64 s[0:1], -1, 0
	v_writelane_b32 v237, s0, 45
	s_cmp_eq_u32 s30, 8
	s_nop 0
	v_writelane_b32 v237, s1, 46
	s_cselect_b64 s[0:1], -1, 0
	v_writelane_b32 v237, s0, 47
	s_cmp_eq_u32 s30, 9
	s_nop 0
	v_writelane_b32 v237, s1, 48
	s_cselect_b64 s[0:1], -1, 0
	v_writelane_b32 v237, s0, 49
	s_cmp_eq_u32 s30, 10
	s_nop 0
	v_writelane_b32 v237, s1, 50
	s_cselect_b64 s[0:1], -1, 0
	v_writelane_b32 v237, s0, 51
	s_cmp_eq_u32 s30, 11
	s_nop 0
	v_writelane_b32 v237, s1, 52
	s_cselect_b64 s[0:1], -1, 0
	v_writelane_b32 v237, s0, 53
	s_cmp_eq_u32 s30, 12
	s_nop 0
	v_writelane_b32 v237, s1, 54
	s_cselect_b64 s[0:1], -1, 0
	v_writelane_b32 v237, s0, 55
	s_cmp_eq_u32 s30, 13
	s_nop 0
	v_writelane_b32 v237, s1, 56
	s_cselect_b64 s[0:1], -1, 0
	v_writelane_b32 v237, s0, 57
	s_cmp_eq_u32 s30, 14
	s_nop 0
	v_writelane_b32 v237, s1, 58
	s_cselect_b64 s[0:1], -1, 0
	v_writelane_b32 v237, s0, 59
	s_cmp_eq_u32 s30, 15
	s_nop 0
	v_writelane_b32 v237, s1, 60
	s_cselect_b64 s[0:1], -1, 0
	v_writelane_b32 v237, s0, 61
	s_nop 1
	v_writelane_b32 v237, s1, 62
	s_add_u32 s0, s94, 0x48e4400
	s_addc_u32 s1, s95, 0
	v_writelane_b32 v237, s0, 63
	s_nop 1
	v_writelane_b32 v236, s1, 0
	s_add_u32 s0, s94, 0x48e4500
	s_addc_u32 s1, s95, 0
	v_writelane_b32 v236, s0, 1
	s_cmpk_lt_i32 s64, 0x600
	s_nop 0
	v_writelane_b32 v236, s1, 2
	s_cselect_b64 s[0:1], -1, 0
	s_add_u32 s46, s94, 0x198e8000
	v_writelane_b32 v236, s0, 3
	s_addc_u32 s47, s95, 0
	s_nop 0
	v_writelane_b32 v236, s1, 4
	s_add_u32 s0, s94, 0x1b0e8000
	s_addc_u32 s1, s95, 0
	v_writelane_b32 v236, s0, 5
	s_nop 1
	v_writelane_b32 v236, s1, 6
	s_add_u32 s0, s94, 0x1d148000
	v_writelane_b32 v236, s0, 7
	s_addc_u32 s0, s95, 0
	v_writelane_b32 v236, s0, 8
	s_add_u32 s0, s94, 0x1e148000
	v_writelane_b32 v236, s0, 9
	s_addc_u32 s0, s95, 0
	v_writelane_b32 v236, s0, 10
	s_add_u32 s0, s94, 0x2080000
	v_writelane_b32 v236, s0, 11
	s_addc_u32 s0, s95, 0
	v_writelane_b32 v236, s0, 12
	s_add_u32 s0, s94, 0x20a0000
	v_writelane_b32 v236, s0, 13
	s_addc_u32 s0, s95, 0
	v_writelane_b32 v236, s0, 14
	s_add_u32 s0, s94, 0x1f148000
	s_addc_u32 s1, s95, 0
	v_writelane_b32 v236, s0, 15
	s_nop 1
	v_writelane_b32 v236, s1, 16
	s_add_u32 s0, s94, 0x1f1c8000
	v_writelane_b32 v236, s0, 17
	s_addc_u32 s0, s95, 0
	v_writelane_b32 v236, s0, 18
	s_lshl_b32 s0, s64, 8
	v_writelane_b32 v236, s0, 19
	s_lshl_b32 s0, s2, 8
	v_writelane_b32 v236, s0, 20
	s_lshl_b64 s[0:1], s[64:65], 8
	v_writelane_b32 v236, s0, 21
	s_nop 1
	v_writelane_b32 v236, s1, 22
	s_lshl_b64 s[0:1], s[2:3], 8
	v_writelane_b32 v236, s0, 23
	s_nop 1
	v_writelane_b32 v236, s1, 24
	s_lshl_b64 s[0:1], s[64:65], 13
	s_add_u32 s4, s72, s0
	s_addc_u32 s5, s73, s1
	s_add_u32 s4, s4, 0x2000000
	s_addc_u32 s5, s5, 0
	v_writelane_b32 v236, s4, 25
	s_lshl_b64 s[76:77], s[2:3], 13
	s_nop 0
	v_writelane_b32 v236, s5, 26
	s_lshl_b64 s[4:5], s[64:65], 12
	s_add_u32 s24, s94, s4
	s_addc_u32 s25, s95, s5
	s_add_u32 s4, s24, 0x58e8000
	s_addc_u32 s5, s25, 0
	v_writelane_b32 v236, s4, 27
	s_nop 1
	v_writelane_b32 v236, s5, 28
	s_lshl_b64 s[4:5], s[2:3], 12
	s_add_u32 s0, s54, s0
	s_addc_u32 s1, s55, s1
	s_add_u32 s0, s0, 16
	s_addc_u32 s1, s1, 0
	v_writelane_b32 v236, s0, 29
	s_nop 1
	v_writelane_b32 v236, s1, 30
	s_add_u32 s0, s24, 0x1e00000
	s_addc_u32 s1, s25, 0
	v_writelane_b32 v236, s0, 31
	s_lshl_b32 s3, s2, 1
	s_lshl_b32 s24, s2, 6
	v_writelane_b32 v236, s1, 32
	s_lshl_b32 s0, s64, 1
	v_writelane_b32 v236, s0, 33
	s_lshl_b32 s0, s64, 2
	v_writelane_b32 v236, s0, 34
	s_lshl_b32 s0, s64, 6
	v_writelane_b32 v236, s0, 35
	s_mov_b32 s0, s64
	v_writelane_b32 v236, s0, 36
	s_movk_i32 s25, 0x48
	s_nop 0
	v_writelane_b32 v236, s1, 37
	s_lshl_b32 s0, s64, 11
	v_writelane_b32 v236, s0, 38
	s_lshl_b32 s0, s2, 11
	v_writelane_b32 v236, s0, 39
	s_mov_b32 s1, 0
	s_lshl_b32 s0, s2, 2
	v_writelane_b32 v236, s0, 40
	s_nop 1
	v_writelane_b32 v236, s1, 41
	v_writelane_b32 v236, s8, 42
	s_nop 1
	v_writelane_b32 v236, s9, 43
	v_writelane_b32 v236, s20, 44
	s_nop 1
	v_writelane_b32 v236, s21, 45
	v_writelane_b32 v236, s16, 46
	s_nop 1
	v_writelane_b32 v236, s17, 47
	v_writelane_b32 v236, s18, 48
	s_nop 1
	v_writelane_b32 v236, s19, 49
	v_writelane_b32 v236, s14, 50
	v_writelane_b32 v236, s74, 51
	s_nop 1
	v_writelane_b32 v236, s75, 52
	v_writelane_b32 v236, s46, 53
	s_nop 1
	v_writelane_b32 v236, s47, 54
	s_branch .LBB0_121
